# P8 K-loop: next trip's head test folded into the tail (one taken branch per trip instead of two), on top of v100
# baseline (speedup 1.0000x reference)
.Lp8_hook:
	s_mov_b64 s[50:51], 0
	v_mov_b32_e32 v157, v148
	v_mov_b32_e32 v158, v0

.LBB0_1003:
	v_add_u32_e32 v130, 0x10000, v155
	ds_read_b128 v[132:135], v130
	ds_read_b128 v[144:147], v130 offset:1024
	ds_read_b128 v[158:161], v130 offset:2048
	ds_read_b128 v[162:165], v130 offset:3072
	v_add_u32_e32 v130, 0x14000, v155
	s_lshl_b32 s39, s92, 7
	ds_read_b128 v[166:169], v130
	ds_read_b128 v[170:173], v130 offset:1024
	ds_read_b128 v[174:177], v130 offset:2048
	ds_read_b128 v[178:181], v130 offset:3072
	s_add_i32 s93, s61, s39
	s_addk_i32 s39, 0x100
	s_add_i32 s94, s93, 0x80
	s_add_i32 s95, s39, s61
	s_and_b64 s[50:51], s[48:49], exec
	s_cselect_b32 s50, s87, s95
	s_add_i32 s39, s39, s63
	s_and_b64 s[48:49], s[48:49], exec
	s_cselect_b32 s48, s88, s39
	s_or_b32 s49, s48, 0x80
	s_mov_b32 m0, s77
	ds_read_b128 v[182:185], v156
	ds_read_b128 v[186:189], v156 offset:1024
	buffer_load_dwordx4 v151, s[28:31], s94 offen lds
	s_mov_b32 m0, s78
	ds_read_b128 v[190:193], v156 offset:2048
	ds_read_b128 v[194:197], v156 offset:3072
	buffer_load_dwordx4 v153, s[28:31], s94 offen lds
	s_add_i32 s93, s93, 0x160080
	s_mov_b32 m0, s79
	ds_read_b128 v[198:201], v156 offset:4096
	ds_read_b128 v[202:205], v156 offset:5120
	buffer_load_dwordx4 v151, s[28:31], s93 offen lds
	s_mov_b32 m0, s80
	ds_read_b128 v[206:209], v156 offset:6144
	ds_read_b128 v[210:213], v156 offset:7168
	buffer_load_dwordx4 v153, s[28:31], s93 offen lds
	s_waitcnt vmcnt(8)
	s_waitcnt lgkmcnt(0)
	s_barrier
	s_waitcnt lgkmcnt(0)
	v_mfma_f32_16x16x32_bf16 v[126:129], v[132:135], v[182:185], v[126:129]
	v_mfma_f32_16x16x32_bf16 v[126:129], v[144:147], v[186:189], v[126:129]
	v_mfma_f32_16x16x32_bf16 v[110:113], v[144:147], v[194:197], v[110:113]
	v_mfma_f32_16x16x32_bf16 v[110:113], v[132:135], v[190:193], v[110:113]
	v_mfma_f32_16x16x32_bf16 v[94:97], v[132:135], v[198:201], v[94:97]
	v_mfma_f32_16x16x32_bf16 v[94:97], v[144:147], v[202:205], v[94:97]
	v_mfma_f32_16x16x32_bf16 v[78:81], v[144:147], v[210:213], v[78:81]
	v_mfma_f32_16x16x32_bf16 v[78:81], v[132:135], v[206:209], v[78:81]
	v_mfma_f32_16x16x32_bf16 v[74:77], v[162:165], v[210:213], v[74:77]
	v_mfma_f32_16x16x32_bf16 v[74:77], v[158:161], v[206:209], v[74:77]
	v_mfma_f32_16x16x32_bf16 v[90:93], v[158:161], v[198:201], v[90:93]
	v_mfma_f32_16x16x32_bf16 v[90:93], v[162:165], v[202:205], v[90:93]
	v_mfma_f32_16x16x32_bf16 v[106:109], v[162:165], v[194:197], v[106:109]
	v_mfma_f32_16x16x32_bf16 v[106:109], v[158:161], v[190:193], v[106:109]
	v_mfma_f32_16x16x32_bf16 v[122:125], v[158:161], v[182:185], v[122:125]
	v_mfma_f32_16x16x32_bf16 v[122:125], v[162:165], v[186:189], v[122:125]
	v_mfma_f32_16x16x32_bf16 v[118:121], v[166:169], v[182:185], v[118:121]
	v_mfma_f32_16x16x32_bf16 v[118:121], v[170:173], v[186:189], v[118:121]
	v_mfma_f32_16x16x32_bf16 v[102:105], v[170:173], v[194:197], v[102:105]
	v_mfma_f32_16x16x32_bf16 v[102:105], v[166:169], v[190:193], v[102:105]
	v_mfma_f32_16x16x32_bf16 v[86:89], v[166:169], v[198:201], v[86:89]
	v_mfma_f32_16x16x32_bf16 v[86:89], v[170:173], v[202:205], v[86:89]
	v_mfma_f32_16x16x32_bf16 v[70:73], v[170:173], v[210:213], v[70:73]
	v_mfma_f32_16x16x32_bf16 v[70:73], v[166:169], v[206:209], v[70:73]
	v_mfma_f32_16x16x32_bf16 v[66:69], v[178:181], v[210:213], v[66:69]
	v_mfma_f32_16x16x32_bf16 v[66:69], v[174:177], v[206:209], v[66:69]
	v_mfma_f32_16x16x32_bf16 v[82:85], v[174:177], v[198:201], v[82:85]
	v_mfma_f32_16x16x32_bf16 v[82:85], v[178:181], v[202:205], v[82:85]
	v_mfma_f32_16x16x32_bf16 v[98:101], v[178:181], v[194:197], v[98:101]
	v_mfma_f32_16x16x32_bf16 v[98:101], v[174:177], v[190:193], v[98:101]
	v_mfma_f32_16x16x32_bf16 v[114:117], v[174:177], v[182:185], v[114:117]
	v_mfma_f32_16x16x32_bf16 v[114:117], v[178:181], v[186:189], v[114:117]
	s_barrier
	s_mov_b32 m0, s64
	s_mov_b32 s39, s31
	ds_read_b128 v[182:185], v156 offset:16384
	ds_read_b128 v[186:189], v156 offset:17408
	buffer_load_dwordx4 v152, s[36:39], s48 offen lds
	s_mov_b32 m0, s65
	ds_read_b128 v[190:193], v156 offset:18432
	ds_read_b128 v[194:197], v156 offset:19456
	buffer_load_dwordx4 v154, s[36:39], s48 offen lds
	s_add_i32 s51, s48, 0x160000
	s_mov_b32 m0, s66
	ds_read_b128 v[198:201], v156 offset:20480
	ds_read_b128 v[202:205], v156 offset:21504
	buffer_load_dwordx4 v152, s[36:39], s51 offen lds
	s_mov_b32 m0, s67
	ds_read_b128 v[206:209], v156 offset:22528
	ds_read_b128 v[210:213], v156 offset:23552
	buffer_load_dwordx4 v154, s[36:39], s51 offen lds
	s_waitcnt vmcnt(6)
	s_waitcnt lgkmcnt(0)
	s_barrier
	s_waitcnt lgkmcnt(0)
	v_mfma_f32_16x16x32_bf16 v[62:65], v[132:135], v[182:185], v[62:65]
	v_mfma_f32_16x16x32_bf16 v[62:65], v[144:147], v[186:189], v[62:65]
	v_mfma_f32_16x16x32_bf16 v[46:49], v[144:147], v[194:197], v[46:49]
	v_mfma_f32_16x16x32_bf16 v[46:49], v[132:135], v[190:193], v[46:49]
	v_mfma_f32_16x16x32_bf16 v[30:33], v[132:135], v[198:201], v[30:33]
	v_mfma_f32_16x16x32_bf16 v[30:33], v[144:147], v[202:205], v[30:33]
	v_mfma_f32_16x16x32_bf16 v[14:17], v[144:147], v[210:213], v[14:17]
	v_mfma_f32_16x16x32_bf16 v[14:17], v[132:135], v[206:209], v[14:17]
	v_mfma_f32_16x16x32_bf16 v[10:13], v[162:165], v[210:213], v[10:13]
	v_mfma_f32_16x16x32_bf16 v[10:13], v[158:161], v[206:209], v[10:13]
	v_mfma_f32_16x16x32_bf16 v[26:29], v[158:161], v[198:201], v[26:29]
	v_mfma_f32_16x16x32_bf16 v[26:29], v[162:165], v[202:205], v[26:29]
	v_mfma_f32_16x16x32_bf16 v[42:45], v[162:165], v[194:197], v[42:45]
	v_mfma_f32_16x16x32_bf16 v[42:45], v[158:161], v[190:193], v[42:45]
	v_mfma_f32_16x16x32_bf16 v[58:61], v[158:161], v[182:185], v[58:61]
	v_mfma_f32_16x16x32_bf16 v[58:61], v[162:165], v[186:189], v[58:61]
	v_mfma_f32_16x16x32_bf16 v[54:57], v[166:169], v[182:185], v[54:57]
	v_mfma_f32_16x16x32_bf16 v[54:57], v[170:173], v[186:189], v[54:57]
	v_mfma_f32_16x16x32_bf16 v[38:41], v[170:173], v[194:197], v[38:41]
	v_mfma_f32_16x16x32_bf16 v[38:41], v[166:169], v[190:193], v[38:41]
	v_mfma_f32_16x16x32_bf16 v[22:25], v[166:169], v[198:201], v[22:25]
	v_mfma_f32_16x16x32_bf16 v[22:25], v[170:173], v[202:205], v[22:25]
	v_mfma_f32_16x16x32_bf16 v[6:9], v[170:173], v[210:213], v[6:9]
	v_mfma_f32_16x16x32_bf16 v[6:9], v[166:169], v[206:209], v[6:9]
	v_mfma_f32_16x16x32_bf16 v[2:5], v[178:181], v[210:213], v[2:5]
	v_mfma_f32_16x16x32_bf16 v[2:5], v[174:177], v[206:209], v[2:5]
	v_mfma_f32_16x16x32_bf16 v[18:21], v[174:177], v[198:201], v[18:21]
	v_mfma_f32_16x16x32_bf16 v[18:21], v[178:181], v[202:205], v[18:21]
	v_mfma_f32_16x16x32_bf16 v[34:37], v[178:181], v[194:197], v[34:37]
	v_mfma_f32_16x16x32_bf16 v[34:37], v[174:177], v[190:193], v[34:37]
	v_mfma_f32_16x16x32_bf16 v[50:53], v[174:177], v[182:185], v[50:53]
	v_mfma_f32_16x16x32_bf16 v[50:53], v[178:181], v[186:189], v[50:53]
	s_barrier
	v_add_u32_e32 v130, 0x18000, v155
	ds_read_b128 v[132:135], v130
	ds_read_b128 v[144:147], v130 offset:1024
	ds_read_b128 v[158:161], v130 offset:2048
	ds_read_b128 v[162:165], v130 offset:3072
	v_add_u32_e32 v130, 0x1c000, v155
	ds_read_b128 v[166:169], v130
	ds_read_b128 v[170:173], v130 offset:1024
	ds_read_b128 v[174:177], v130 offset:2048
	ds_read_b128 v[178:181], v130 offset:3072
	s_mov_b32 m0, s62
	ds_read_b128 v[182:185], v156 offset:32768
	ds_read_b128 v[186:189], v156 offset:33792
	buffer_load_dwordx4 v151, s[28:31], s50 offen lds
	s_mov_b32 m0, s68
	ds_read_b128 v[190:193], v156 offset:34816
	ds_read_b128 v[194:197], v156 offset:35840
	buffer_load_dwordx4 v153, s[28:31], s50 offen lds
	s_add_i32 s50, s50, 0x160000
	s_mov_b32 m0, s69
	ds_read_b128 v[198:201], v156 offset:36864
	ds_read_b128 v[202:205], v156 offset:37888
	buffer_load_dwordx4 v151, s[28:31], s50 offen lds
	s_mov_b32 m0, s70
	ds_read_b128 v[206:209], v156 offset:38912
	ds_read_b128 v[210:213], v156 offset:39936
	buffer_load_dwordx4 v153, s[28:31], s50 offen lds
	s_waitcnt vmcnt(8)
	s_waitcnt lgkmcnt(0)
	s_barrier
	s_waitcnt lgkmcnt(0)
	v_mfma_f32_16x16x32_bf16 v[126:129], v[132:135], v[182:185], v[126:129]
	v_mfma_f32_16x16x32_bf16 v[126:129], v[144:147], v[186:189], v[126:129]
	v_mfma_f32_16x16x32_bf16 v[110:113], v[144:147], v[194:197], v[110:113]
	v_mfma_f32_16x16x32_bf16 v[110:113], v[132:135], v[190:193], v[110:113]
	v_mfma_f32_16x16x32_bf16 v[94:97], v[132:135], v[198:201], v[94:97]
	v_mfma_f32_16x16x32_bf16 v[94:97], v[144:147], v[202:205], v[94:97]
	v_mfma_f32_16x16x32_bf16 v[78:81], v[144:147], v[210:213], v[78:81]
	v_mfma_f32_16x16x32_bf16 v[78:81], v[132:135], v[206:209], v[78:81]
	v_mfma_f32_16x16x32_bf16 v[74:77], v[162:165], v[210:213], v[74:77]
	v_mfma_f32_16x16x32_bf16 v[74:77], v[158:161], v[206:209], v[74:77]
	v_mfma_f32_16x16x32_bf16 v[90:93], v[158:161], v[198:201], v[90:93]
	v_mfma_f32_16x16x32_bf16 v[90:93], v[162:165], v[202:205], v[90:93]
	v_mfma_f32_16x16x32_bf16 v[106:109], v[162:165], v[194:197], v[106:109]
	v_mfma_f32_16x16x32_bf16 v[106:109], v[158:161], v[190:193], v[106:109]
	v_mfma_f32_16x16x32_bf16 v[122:125], v[158:161], v[182:185], v[122:125]
	v_mfma_f32_16x16x32_bf16 v[122:125], v[162:165], v[186:189], v[122:125]
	v_mfma_f32_16x16x32_bf16 v[118:121], v[166:169], v[182:185], v[118:121]
	v_mfma_f32_16x16x32_bf16 v[118:121], v[170:173], v[186:189], v[118:121]
	v_mfma_f32_16x16x32_bf16 v[102:105], v[170:173], v[194:197], v[102:105]
	v_mfma_f32_16x16x32_bf16 v[102:105], v[166:169], v[190:193], v[102:105]
	v_mfma_f32_16x16x32_bf16 v[86:89], v[166:169], v[198:201], v[86:89]
	v_mfma_f32_16x16x32_bf16 v[86:89], v[170:173], v[202:205], v[86:89]
	v_mfma_f32_16x16x32_bf16 v[70:73], v[170:173], v[210:213], v[70:73]
	v_mfma_f32_16x16x32_bf16 v[70:73], v[166:169], v[206:209], v[70:73]
	v_mfma_f32_16x16x32_bf16 v[66:69], v[178:181], v[210:213], v[66:69]
	v_mfma_f32_16x16x32_bf16 v[66:69], v[174:177], v[206:209], v[66:69]
	v_mfma_f32_16x16x32_bf16 v[82:85], v[174:177], v[198:201], v[82:85]
	v_mfma_f32_16x16x32_bf16 v[82:85], v[178:181], v[202:205], v[82:85]
	v_mfma_f32_16x16x32_bf16 v[98:101], v[178:181], v[194:197], v[98:101]
	v_mfma_f32_16x16x32_bf16 v[98:101], v[174:177], v[190:193], v[98:101]
	v_mfma_f32_16x16x32_bf16 v[114:117], v[174:177], v[182:185], v[114:117]
	v_mfma_f32_16x16x32_bf16 v[114:117], v[178:181], v[186:189], v[114:117]
	s_barrier
	s_mov_b32 m0, s72
	ds_read_b128 v[182:185], v156 offset:49152
	ds_read_b128 v[186:189], v156 offset:50176
	buffer_load_dwordx4 v152, s[36:39], s49 offen lds
	s_mov_b32 m0, s73
	ds_read_b128 v[190:193], v156 offset:51200
	ds_read_b128 v[194:197], v156 offset:52224
	buffer_load_dwordx4 v154, s[36:39], s49 offen lds
	s_add_i32 s48, s48, 0x160080
	s_mov_b32 m0, s74
	ds_read_b128 v[198:201], v156 offset:53248
	ds_read_b128 v[202:205], v156 offset:54272
	buffer_load_dwordx4 v152, s[36:39], s48 offen lds
	s_mov_b32 m0, s75
	ds_read_b128 v[206:209], v156 offset:55296
	ds_read_b128 v[210:213], v156 offset:56320
	buffer_load_dwordx4 v154, s[36:39], s48 offen lds
	s_waitcnt vmcnt(6)
	s_waitcnt lgkmcnt(0)
	s_barrier
	s_waitcnt lgkmcnt(0)
	v_mfma_f32_16x16x32_bf16 v[62:65], v[132:135], v[182:185], v[62:65]
	v_mfma_f32_16x16x32_bf16 v[62:65], v[144:147], v[186:189], v[62:65]
	v_mfma_f32_16x16x32_bf16 v[46:49], v[144:147], v[194:197], v[46:49]
	v_mfma_f32_16x16x32_bf16 v[46:49], v[132:135], v[190:193], v[46:49]
	v_mfma_f32_16x16x32_bf16 v[30:33], v[132:135], v[198:201], v[30:33]
	v_mfma_f32_16x16x32_bf16 v[30:33], v[144:147], v[202:205], v[30:33]
	v_mfma_f32_16x16x32_bf16 v[14:17], v[144:147], v[210:213], v[14:17]
	v_mfma_f32_16x16x32_bf16 v[14:17], v[132:135], v[206:209], v[14:17]
	v_mfma_f32_16x16x32_bf16 v[10:13], v[162:165], v[210:213], v[10:13]
	v_mfma_f32_16x16x32_bf16 v[10:13], v[158:161], v[206:209], v[10:13]
	v_mfma_f32_16x16x32_bf16 v[26:29], v[158:161], v[198:201], v[26:29]
	v_mfma_f32_16x16x32_bf16 v[26:29], v[162:165], v[202:205], v[26:29]
	v_mfma_f32_16x16x32_bf16 v[42:45], v[162:165], v[194:197], v[42:45]
	v_mfma_f32_16x16x32_bf16 v[42:45], v[158:161], v[190:193], v[42:45]
	v_mfma_f32_16x16x32_bf16 v[58:61], v[158:161], v[182:185], v[58:61]
	v_mfma_f32_16x16x32_bf16 v[58:61], v[162:165], v[186:189], v[58:61]
	v_mfma_f32_16x16x32_bf16 v[54:57], v[166:169], v[182:185], v[54:57]
	v_mfma_f32_16x16x32_bf16 v[54:57], v[170:173], v[186:189], v[54:57]
	v_mfma_f32_16x16x32_bf16 v[38:41], v[170:173], v[194:197], v[38:41]
	v_mfma_f32_16x16x32_bf16 v[38:41], v[166:169], v[190:193], v[38:41]
	v_mfma_f32_16x16x32_bf16 v[22:25], v[166:169], v[198:201], v[22:25]
	v_mfma_f32_16x16x32_bf16 v[22:25], v[170:173], v[202:205], v[22:25]
	v_mfma_f32_16x16x32_bf16 v[6:9], v[170:173], v[210:213], v[6:9]
	v_mfma_f32_16x16x32_bf16 v[6:9], v[166:169], v[206:209], v[6:9]
	v_mfma_f32_16x16x32_bf16 v[2:5], v[178:181], v[210:213], v[2:5]
	v_mfma_f32_16x16x32_bf16 v[2:5], v[174:177], v[206:209], v[2:5]
	v_mfma_f32_16x16x32_bf16 v[18:21], v[174:177], v[198:201], v[18:21]
	v_mfma_f32_16x16x32_bf16 v[18:21], v[178:181], v[202:205], v[18:21]
	v_mfma_f32_16x16x32_bf16 v[34:37], v[178:181], v[194:197], v[34:37]
	v_mfma_f32_16x16x32_bf16 v[34:37], v[174:177], v[190:193], v[34:37]
	v_mfma_f32_16x16x32_bf16 v[50:53], v[174:177], v[182:185], v[50:53]
	v_mfma_f32_16x16x32_bf16 v[50:53], v[178:181], v[186:189], v[50:53]
	s_barrier
	s_add_i32 s39, s92, 2
	s_cmpk_gt_u32 s92, 0x55
	s_cbranch_scc1 .LBB0_1005
	s_mov_b32 s92, s39
	s_cmpk_eq_i32 s92, 0x56
	s_cselect_b64 s[48:49], -1, 0
	s_and_b64 s[50:51], s[6:7], s[48:49]
	s_andn2_b64 vcc, exec, s[50:51]
	s_cbranch_vccnz .LBB0_1003
	s_branch .Lp8_hook
